# v7 plus relaxed row-scale load waits in P2/P12 epilogues (no vmcnt0 before issue, counted vmcnt at commit)
# baseline (speedup 1.0000x reference)
; #define LAS __attribute__((address_space(3)))
; __device__ __forceinline__ int opaque_tid() { int t = threadIdx.x; asm volatile("" : "+v"(t)); return t; }
; #define PG8_SC_ISSUE(U) do { if (SC && tid < 256 && E.sc_rowsq()) { const float* rp_ = E.sc_rowsq() + (size_t)((U).pm * 256 + tid) * 8; pqa = *(const GAS f32x4*)rp_; pqb = *(const GAS f32x4*)(rp_ + 4); } } while (0)
; #define PG8_SC_COMMIT(b_) do { if (SC && tid < 256) { float v_ = 1.f; if (E.sc_rowsq()) v_ = __builtin_amdgcn_rsqf((((pqa.x + pqa.y) + (pqa.z + pqa.w)) + ((pqb.x + pqb.y) + (pqb.z + pqb.w))) * E.sc_inv_n() + EPSN); scb[(b_) * 256 + tid] = v_; } } while (0)
; template <class Epi, class Sched>
; __device__ __forceinline__ void gemm_phase(LAS unsigned char* lds, const Gemm g, const Sched& S, const Epi& E) {
;     ...
;         if (has_next) PG8_SC_ISSUE(nxt);
;         { const int l2 = opaque_tid() & 63; E(acc, cur, wr, wc, l2 & 15, l2 >> 4, (const LAS float*)(scb + (ui & 1) * 256)); }
;         if (has_next) PG8_SC_COMMIT((ui + 1) & 1);
.LBB0_302:
	s_and_b64 s[48:49], s[12:13], s[4:5]
	s_and_saveexec_b64 s[0:1], s[48:49]
	s_cbranch_execz .LBB0_304
	v_lshl_add_u32 v4, s40, 8, v156
	v_ashrrev_i32_e32 v5, 31, v4
	v_lshlrev_b64 v[4:5], 5, v[4:5]
	v_lshl_add_u64 v[8:9], s[16:17], 0, v[4:5]
	global_load_dwordx4 v[4:7], v[8:9], off offset:16
	s_nop 0
	global_load_dwordx4 v[8:11], v[8:9], off

; #define GAS __attribute__((address_space(1)))
; __device__ __forceinline__ unsigned cvtpk(float lo, float hi) { unsigned r; asm volatile("v_cvt_pk_bf16_f32 %0, %1, %2" : "=v"(r) : "v"(lo), "v"(hi)); return r; }
;     __device__ __forceinline__ void operator()(const f32x4 (&acc)[2][2][4][2], const pg8::Unit& u, int wr, int wc, int fr, int fq, const LAS float* scr) const {
;     ...
;                     u32x4 w; w.x = cvtpk(v0[0], v0[1]); w.y = cvtpk(v0[2], v0[3]); w.z = cvtpk(v1[0], v1[1]); w.w = cvtpk(v1[2], v1[3]);
;                     *(GAS u32x4*)(O + (size_t)row * ldc + col0) = w;
.LBB0_548:
	v_cvt_pk_bf16_f32 v16, v16, v17
	v_cvt_pk_bf16_f32 v17, v18, v19
	v_cvt_pk_bf16_f32 v18, v12, v13
	v_lshl_add_u64 v[12:13], v[70:71], 1, v[76:77]
	v_cvt_pk_bf16_f32 v19, v14, v15
	global_store_dwordx4 v[12:13], v[16:19], off offset:256
	s_and_saveexec_b64 s[0:1], s[48:49]
	s_cbranch_execz .LBB0_550
	s_waitcnt vmcnt(16)
	v_mov_b32_e32 v12, v4
	v_mov_b32_e32 v13, v8
	v_mov_b32_e32 v14, v5
	v_mov_b32_e32 v15, v9
	v_pk_add_f32 v[12:13], v[12:13], v[14:15]
	v_mov_b32_e32 v14, v6
	v_mov_b32_e32 v15, v10
	v_mov_b32_e32 v16, v7
	v_mov_b32_e32 v17, v11
	v_pk_add_f32 v[14:15], v[14:15], v[16:17]
	s_lshl_b32 s2, s71, 10
	v_pk_add_f32 v[12:13], v[12:13], v[14:15]
	s_and_b32 s2, s2, 0x400
	v_add_f32_e32 v0, v12, v13
	v_fmamk_f32 v0, v0, 0x3a000000, v241
	v_rsq_f32_e32 v0, v0
	v_add_u32_e32 v12, s2, v158
	ds_write_b32 v12, v0

; #define LAS __attribute__((address_space(3)))
; #define GAS __attribute__((address_space(1)))
;     __device__ __forceinline__ void operator()(const f32x4 (&acc)[2][2][4][2], const pg8::Unit& u, int wr, int wc, int fr, int fq, const LAS float* scr) const {
;         const int row0 = u.pm * 256 + wr * 64 + fr, col0 = u.pn * 128 + wc * 32 + 8 * fq;
; #pragma unroll
;         for (int ai = 0; ai < 2; ++ai)
; #pragma unroll
;             for (int m = 0; m < 4; ++m) { const int row = row0 + ai * 128 + m * 16; float r[8]; const float s_ = scr[ai * 128 + wr * 64 + m * 16 + fr];
;                 const float k_ = -LOG2E * s_, s2_ = s_ * s_;
; #pragma unroll
;                 for (int n = 0; n < 2; ++n)
; #pragma unroll
;                     for (int i = 0; i < 4; ++i) { const float g_ = acc[ai][0][m][n][i], u_ = acc[ai][1][m][n][i];
;                         r[n * 4 + i] = (g_ * u_) * (s2_ * __builtin_amdgcn_rcpf(1.0f + __builtin_amdgcn_exp2f(g_ * k_))); }
;                 typedef float f32x2_ __attribute__((ext_vector_type(2))); typedef __bf16 bf16x2_ __attribute__((ext_vector_type(2)));
;                 u32x4 w;
;                 { const f32x2_ a0 = {r[0], r[1]}, a1 = {r[2], r[3]}, a2 = {r[4], r[5]}, a3 = {r[6], r[7]};
;                   w.x = __builtin_bit_cast(unsigned, __builtin_convertvector(a0, bf16x2_)); w.y = __builtin_bit_cast(unsigned, __builtin_convertvector(a1, bf16x2_));
;                   w.z = __builtin_bit_cast(unsigned, __builtin_convertvector(a2, bf16x2_)); w.w = __builtin_bit_cast(unsigned, __builtin_convertvector(a3, bf16x2_)); }
;                 *(GAS u32x4*)(H + (size_t)row * ldc + col0) = w; }
.LBB0_1894:
	s_and_b64 s[24:25], s[6:7], s[4:5]
	s_and_saveexec_b64 s[0:1], s[24:25]
	s_cbranch_execz .LBB0_1896
	v_lshl_add_u32 v4, s18, 8, v150
	v_ashrrev_i32_e32 v5, 31, v4
	v_lshlrev_b64 v[4:5], 5, v[4:5]
	v_lshl_add_u64 v[8:9], s[8:9], 0, v[4:5]
	global_load_dwordx4 v[4:7], v[8:9], off offset:16
	s_nop 0
	global_load_dwordx4 v[8:11], v[8:9], off
.LBB0_1896:
	s_or_b64 exec, exec, s[0:1]
	v_mov_b32_e32 v148, v240
	s_lshl_b32 s0, s47, 8
	s_add_i32 s0, s0, s39
	v_and_b32_e32 v149, 15, v148
	v_or_b32_e32 v154, s0, v149
	s_lshl_b32 s0, s46, 7
	v_lshrrev_b32_e32 v148, 1, v148
	v_and_or_b32 v148, v148, 24, s0
	s_lshl_b32 s0, s2, 10
	s_and_b32 s0, s0, 0x400
	s_add_i32 s0, s44, s0
	v_lshl_add_u32 v155, v149, 2, s0
	ds_read2_b32 v[156:157], v155 offset1:16
	v_pk_mul_f32 v[130:131], v[126:127], v[130:131]
	v_pk_mul_f32 v[138:139], v[134:135], v[138:139]
	v_or_b32_e32 v148, s40, v148
	v_ashrrev_i32_e32 v149, 31, v148
	s_waitcnt lgkmcnt(0)
	v_mul_f32_e32 v160, 0xbfb8aa3b, v156
	v_mul_f32_e32 v158, v132, v160
	v_mul_f32_e32 v159, v133, v160
	v_exp_f32_e32 v158, v158
	v_exp_f32_e32 v159, v159
	v_mul_f32_e32 v156, v156, v156
	v_pk_mul_f32 v[132:133], v[132:133], v[136:137]
	v_add_f32_e32 v158, 1.0, v158
	v_add_f32_e32 v159, 1.0, v159
	v_rcp_f32_e32 v158, v158
	v_rcp_f32_e32 v159, v159
	v_mul_f32_e32 v126, v126, v160
	v_mul_f32_e32 v127, v127, v160
	v_mul_f32_e32 v134, v134, v160
	v_pk_mul_f32 v[136:137], v[156:157], v[158:159] op_sel_hi:[0,1]
	v_pk_mul_f32 v[132:133], v[132:133], v[136:137]
	v_mul_f32_e32 v136, v124, v160
	v_mul_f32_e32 v137, v125, v160
	v_exp_f32_e32 v136, v136
	v_exp_f32_e32 v137, v137
	v_mul_f32_e32 v135, v135, v160
	v_exp_f32_e32 v126, v126
	v_exp_f32_e32 v127, v127
	v_exp_f32_e32 v134, v134
	v_exp_f32_e32 v135, v135
	v_add_f32_e32 v136, 1.0, v136
	v_add_f32_e32 v137, 1.0, v137
	v_rcp_f32_e32 v136, v136
	v_rcp_f32_e32 v137, v137
	v_add_f32_e32 v126, 1.0, v126
	v_add_f32_e32 v127, 1.0, v127
	v_add_f32_e32 v134, 1.0, v134
	v_add_f32_e32 v135, 1.0, v135
	v_rcp_f32_e32 v126, v126
	v_rcp_f32_e32 v127, v127
	v_rcp_f32_e32 v134, v134
	v_rcp_f32_e32 v135, v135
	v_pk_mul_f32 v[124:125], v[124:125], v[128:129]
	v_pk_mul_f32 v[128:129], v[156:157], v[136:137] op_sel_hi:[0,1]
	v_pk_mul_f32 v[124:125], v[124:125], v[128:129]
	v_pk_mul_f32 v[126:127], v[156:157], v[126:127] op_sel_hi:[0,1]
	v_pk_mul_f32 v[134:135], v[156:157], v[134:135] op_sel_hi:[0,1]
	v_pk_mul_f32 v[126:127], v[130:131], v[126:127]
	v_cvt_pk_bf16_f32 v130, v124, v125
	v_mov_b64_e32 v[124:125], s[12:13]
	s_movk_i32 s2, 0x2c00
	v_pk_mul_f32 v[134:135], v[138:139], v[134:135]
	v_cvt_pk_bf16_f32 v128, v132, v133
	v_cvt_pk_bf16_f32 v131, v126, v127
	v_mad_i64_i32 v[132:133], s[0:1], v154, s2, v[124:125]
	v_lshlrev_b64 v[126:127], 1, v[148:149]
	v_cvt_pk_bf16_f32 v129, v134, v135
	v_lshl_add_u64 v[132:133], v[132:133], 0, v[126:127]
	global_store_dwordx4 v[132:133], v[128:131], off
	v_pk_mul_f32 v[122:123], v[118:119], v[122:123]
	v_pk_mul_f32 v[114:115], v[110:111], v[114:115]
	v_mul_f32_e32 v129, 0xbfb8aa3b, v157
	v_mul_f32_e32 v130, v116, v129
	v_mul_f32_e32 v131, v117, v129
	v_exp_f32_e32 v130, v130
	v_exp_f32_e32 v131, v131
	v_mul_f32_e32 v128, v157, v157
	v_pk_mul_f32 v[116:117], v[116:117], v[120:121]
	v_add_f32_e32 v130, 1.0, v130
	v_add_f32_e32 v131, 1.0, v131
	v_rcp_f32_e32 v130, v130
	v_rcp_f32_e32 v131, v131
	v_mul_f32_e32 v118, v118, v129
	v_mul_f32_e32 v119, v119, v129
	v_exp_f32_e32 v118, v118
	v_pk_mul_f32 v[120:121], v[128:129], v[130:131] op_sel_hi:[0,1]
	v_pk_mul_f32 v[116:117], v[116:117], v[120:121]
	v_mul_f32_e32 v120, v108, v129
	v_mul_f32_e32 v121, v109, v129
	v_exp_f32_e32 v120, v120
	v_exp_f32_e32 v121, v121
	v_pk_mul_f32 v[108:109], v[108:109], v[112:113]
	v_exp_f32_e32 v119, v119
	v_add_f32_e32 v120, 1.0, v120
	v_add_f32_e32 v121, 1.0, v121
	v_rcp_f32_e32 v120, v120
	v_rcp_f32_e32 v121, v121
	v_add_f32_e32 v118, 1.0, v118
	v_add_f32_e32 v119, 1.0, v119
	v_rcp_f32_e32 v118, v118
	v_pk_mul_f32 v[112:113], v[128:129], v[120:121] op_sel_hi:[0,1]
	v_pk_mul_f32 v[112:113], v[108:109], v[112:113]
	v_mul_f32_e32 v108, v110, v129
	v_mul_f32_e32 v109, v111, v129
	v_exp_f32_e32 v108, v108
	v_exp_f32_e32 v109, v109
	v_rcp_f32_e32 v119, v119
	v_or_b32_e32 v120, 16, v154
	v_add_f32_e32 v108, 1.0, v108
	v_add_f32_e32 v109, 1.0, v109
	v_rcp_f32_e32 v108, v108
	v_rcp_f32_e32 v109, v109
	v_pk_mul_f32 v[118:119], v[128:129], v[118:119] op_sel_hi:[0,1]
	v_pk_mul_f32 v[118:119], v[122:123], v[118:119]
	v_cvt_pk_bf16_f32 v110, v112, v113
	v_pk_mul_f32 v[108:109], v[128:129], v[108:109] op_sel_hi:[0,1]
	v_pk_mul_f32 v[114:115], v[114:115], v[108:109]
	v_mad_i64_i32 v[112:113], s[0:1], v120, s2, v[124:125]
	v_cvt_pk_bf16_f32 v108, v116, v117
	v_cvt_pk_bf16_f32 v109, v118, v119
	v_cvt_pk_bf16_f32 v111, v114, v115
	v_lshl_add_u64 v[112:113], v[112:113], 0, v[126:127]
	global_store_dwordx4 v[112:113], v[108:111], off
	ds_read2_b32 v[108:109], v155 offset0:32 offset1:48
	v_pk_mul_f32 v[106:107], v[102:103], v[106:107]
	v_pk_mul_f32 v[98:99], v[94:95], v[98:99]
	v_pk_mul_f32 v[90:91], v[86:87], v[90:91]
	v_pk_mul_f32 v[82:83], v[78:79], v[82:83]
	s_waitcnt lgkmcnt(0)
; #define GAS __attribute__((address_space(1)))
;     __device__ __forceinline__ void operator()(const f32x4 (&acc)[2][2][4][2], const pg8::Unit& u, int wr, int wc, int fr, int fq, const LAS float* scr) const {
;     ...
;             for (int m = 0; m < 4; ++m) { const int row = row0 + ai * 128 + m * 16; float r[8]; const float s_ = scr[ai * 128 + wr * 64 + m * 16 + fr];
;                 const float k_ = -LOG2E * s_, s2_ = s_ * s_;
; #pragma unroll
;                 for (int n = 0; n < 2; ++n)
; #pragma unroll
;                     for (int i = 0; i < 4; ++i) { const float g_ = acc[ai][0][m][n][i], u_ = acc[ai][1][m][n][i];
;                         r[n * 4 + i] = (g_ * u_) * (s2_ * __builtin_amdgcn_rcpf(1.0f + __builtin_amdgcn_exp2f(g_ * k_))); }
;                 typedef float f32x2_ __attribute__((ext_vector_type(2))); typedef __bf16 bf16x2_ __attribute__((ext_vector_type(2)));
;                 u32x4 w;
;                 { const f32x2_ a0 = {r[0], r[1]}, a1 = {r[2], r[3]}, a2 = {r[4], r[5]}, a3 = {r[6], r[7]};
;                   w.x = __builtin_bit_cast(unsigned, __builtin_convertvector(a0, bf16x2_)); w.y = __builtin_bit_cast(unsigned, __builtin_convertvector(a1, bf16x2_));
;                   w.z = __builtin_bit_cast(unsigned, __builtin_convertvector(a2, bf16x2_)); w.w = __builtin_bit_cast(unsigned, __builtin_convertvector(a3, bf16x2_)); }
;                 *(GAS u32x4*)(H + (size_t)row * ldc + col0) = w; }
	v_mul_f32_e32 v112, 0xbfb8aa3b, v108
	v_mul_f32_e32 v110, v100, v112
	v_mul_f32_e32 v111, v101, v112
	v_exp_f32_e32 v110, v110
	v_exp_f32_e32 v111, v111
	v_mul_f32_e32 v108, v108, v108
	v_pk_mul_f32 v[100:101], v[100:101], v[104:105]
	v_add_f32_e32 v110, 1.0, v110
	v_add_f32_e32 v111, 1.0, v111
	v_rcp_f32_e32 v110, v110
	v_rcp_f32_e32 v111, v111
	v_mul_f32_e32 v102, v102, v112
	v_mul_f32_e32 v103, v103, v112
	v_exp_f32_e32 v102, v102
	v_pk_mul_f32 v[104:105], v[108:109], v[110:111] op_sel_hi:[0,1]
	v_pk_mul_f32 v[100:101], v[100:101], v[104:105]
	v_mul_f32_e32 v104, v92, v112
	v_mul_f32_e32 v105, v93, v112
	v_exp_f32_e32 v104, v104
	v_exp_f32_e32 v105, v105
	v_pk_mul_f32 v[92:93], v[92:93], v[96:97]
	v_exp_f32_e32 v103, v103
	v_add_f32_e32 v104, 1.0, v104
	v_add_f32_e32 v105, 1.0, v105
	v_rcp_f32_e32 v104, v104
	v_rcp_f32_e32 v105, v105
	v_add_f32_e32 v102, 1.0, v102
	v_add_f32_e32 v103, 1.0, v103
	v_rcp_f32_e32 v102, v102
	v_pk_mul_f32 v[96:97], v[108:109], v[104:105] op_sel_hi:[0,1]
	v_pk_mul_f32 v[96:97], v[92:93], v[96:97]
	v_mul_f32_e32 v92, v94, v112
	v_mul_f32_e32 v93, v95, v112
	v_exp_f32_e32 v92, v92
	v_exp_f32_e32 v93, v93
	v_rcp_f32_e32 v103, v103
	v_or_b32_e32 v104, 32, v154
	v_add_f32_e32 v92, 1.0, v92
	v_add_f32_e32 v93, 1.0, v93
	v_rcp_f32_e32 v92, v92
	v_rcp_f32_e32 v93, v93
	v_pk_mul_f32 v[102:103], v[108:109], v[102:103] op_sel_hi:[0,1]
	v_pk_mul_f32 v[102:103], v[106:107], v[102:103]
	v_cvt_pk_bf16_f32 v94, v96, v97
	v_pk_mul_f32 v[92:93], v[108:109], v[92:93] op_sel_hi:[0,1]
	v_pk_mul_f32 v[98:99], v[98:99], v[92:93]
	v_mad_i64_i32 v[96:97], s[0:1], v104, s2, v[124:125]
	v_cvt_pk_bf16_f32 v92, v100, v101
	v_cvt_pk_bf16_f32 v93, v102, v103
	v_cvt_pk_bf16_f32 v95, v98, v99
	v_lshl_add_u64 v[96:97], v[96:97], 0, v[126:127]
	global_store_dwordx4 v[96:97], v[92:95], off
	v_pk_mul_f32 v[74:75], v[70:71], v[74:75]
	v_pk_mul_f32 v[66:67], v[62:63], v[66:67]
	v_mul_f32_e32 v93, 0xbfb8aa3b, v109
	v_mul_f32_e32 v94, v84, v93
	v_mul_f32_e32 v95, v85, v93
	v_exp_f32_e32 v94, v94
	v_exp_f32_e32 v95, v95
	v_mul_f32_e32 v92, v109, v109
	v_pk_mul_f32 v[84:85], v[84:85], v[88:89]
	v_add_f32_e32 v94, 1.0, v94
	v_add_f32_e32 v95, 1.0, v95
	v_rcp_f32_e32 v94, v94
	v_rcp_f32_e32 v95, v95
	v_mul_f32_e32 v86, v86, v93
	v_mul_f32_e32 v87, v87, v93
	v_exp_f32_e32 v86, v86
	v_pk_mul_f32 v[88:89], v[92:93], v[94:95] op_sel_hi:[0,1]
	v_pk_mul_f32 v[84:85], v[84:85], v[88:89]
	v_mul_f32_e32 v88, v76, v93
	v_mul_f32_e32 v89, v77, v93
	v_exp_f32_e32 v88, v88
	v_exp_f32_e32 v89, v89
	v_pk_mul_f32 v[76:77], v[76:77], v[80:81]
	v_exp_f32_e32 v87, v87
	v_add_f32_e32 v88, 1.0, v88
	v_add_f32_e32 v89, 1.0, v89
	v_rcp_f32_e32 v88, v88
	v_rcp_f32_e32 v89, v89
	v_add_f32_e32 v86, 1.0, v86
	v_add_f32_e32 v87, 1.0, v87
	v_rcp_f32_e32 v86, v86
	v_pk_mul_f32 v[80:81], v[92:93], v[88:89] op_sel_hi:[0,1]
	v_pk_mul_f32 v[80:81], v[76:77], v[80:81]
	v_mul_f32_e32 v76, v78, v93
	v_mul_f32_e32 v77, v79, v93
	v_exp_f32_e32 v76, v76
	v_exp_f32_e32 v77, v77
	v_rcp_f32_e32 v87, v87
	v_or_b32_e32 v88, 48, v154
	v_add_f32_e32 v76, 1.0, v76
	v_add_f32_e32 v77, 1.0, v77
	v_rcp_f32_e32 v76, v76
	v_rcp_f32_e32 v77, v77
	v_pk_mul_f32 v[86:87], v[92:93], v[86:87] op_sel_hi:[0,1]
	v_pk_mul_f32 v[86:87], v[90:91], v[86:87]
	v_cvt_pk_bf16_f32 v78, v80, v81
	v_pk_mul_f32 v[76:77], v[92:93], v[76:77] op_sel_hi:[0,1]
	v_pk_mul_f32 v[82:83], v[82:83], v[76:77]
	v_mad_i64_i32 v[80:81], s[0:1], v88, s2, v[124:125]
	v_cvt_pk_bf16_f32 v76, v84, v85
	v_cvt_pk_bf16_f32 v77, v86, v87
	v_cvt_pk_bf16_f32 v79, v82, v83
	v_lshl_add_u64 v[80:81], v[80:81], 0, v[126:127]
	global_store_dwordx4 v[80:81], v[76:79], off
	ds_read2_b32 v[76:77], v155 offset0:128 offset1:144
	v_add_u32_e32 v80, 0x80, v154
	v_pk_mul_f32 v[58:59], v[54:55], v[58:59]
	v_pk_mul_f32 v[50:51], v[46:47], v[50:51]
	v_pk_mul_f32 v[42:43], v[38:39], v[42:43]
	s_waitcnt lgkmcnt(0)
	v_mul_f32_e32 v81, 0xbfb8aa3b, v76
	v_mul_f32_e32 v78, v68, v81
	v_mul_f32_e32 v79, v69, v81
	v_exp_f32_e32 v78, v78
	v_exp_f32_e32 v79, v79
	v_mul_f32_e32 v76, v76, v76
	v_pk_mul_f32 v[68:69], v[68:69], v[72:73]
	v_add_f32_e32 v78, 1.0, v78
	v_add_f32_e32 v79, 1.0, v79
	v_rcp_f32_e32 v78, v78
	v_rcp_f32_e32 v79, v79
	v_mul_f32_e32 v70, v70, v81
	v_mul_f32_e32 v71, v71, v81
	v_exp_f32_e32 v70, v70
	v_pk_mul_f32 v[72:73], v[76:77], v[78:79] op_sel_hi:[0,1]
	v_pk_mul_f32 v[68:69], v[68:69], v[72:73]
	v_mul_f32_e32 v72, v60, v81
	v_mul_f32_e32 v73, v61, v81
	v_exp_f32_e32 v72, v72
	v_exp_f32_e32 v73, v73
	v_pk_mul_f32 v[60:61], v[60:61], v[64:65]
	v_exp_f32_e32 v71, v71
	v_add_f32_e32 v72, 1.0, v72
	v_add_f32_e32 v73, 1.0, v73
	v_rcp_f32_e32 v72, v72
	v_rcp_f32_e32 v73, v73
	v_add_f32_e32 v70, 1.0, v70
	v_add_f32_e32 v71, 1.0, v71
	v_rcp_f32_e32 v70, v70
	v_pk_mul_f32 v[64:65], v[76:77], v[72:73] op_sel_hi:[0,1]
	v_pk_mul_f32 v[64:65], v[60:61], v[64:65]
	v_mul_f32_e32 v60, v62, v81
	v_mul_f32_e32 v61, v63, v81
	v_exp_f32_e32 v60, v60
	v_exp_f32_e32 v61, v61
	v_rcp_f32_e32 v71, v71
	v_cvt_pk_bf16_f32 v62, v64, v65
	v_add_f32_e32 v60, 1.0, v60
	v_add_f32_e32 v61, 1.0, v61
	v_rcp_f32_e32 v60, v60
	v_rcp_f32_e32 v61, v61
	v_pk_mul_f32 v[70:71], v[76:77], v[70:71] op_sel_hi:[0,1]
	v_pk_mul_f32 v[70:71], v[74:75], v[70:71]
	v_mad_i64_i32 v[64:65], s[0:1], v80, s2, v[124:125]
	v_pk_mul_f32 v[60:61], v[76:77], v[60:61] op_sel_hi:[0,1]
	v_pk_mul_f32 v[66:67], v[66:67], v[60:61]
	v_cvt_pk_bf16_f32 v60, v68, v69
	v_cvt_pk_bf16_f32 v61, v70, v71
	v_cvt_pk_bf16_f32 v63, v66, v67
	v_lshl_add_u64 v[64:65], v[64:65], 0, v[126:127]
	global_store_dwordx4 v[64:65], v[60:63], off
	v_pk_mul_f32 v[34:35], v[30:31], v[34:35]
	v_pk_mul_f32 v[12:13], v[16:17], v[12:13]
; #define GAS __attribute__((address_space(1)))
;     __device__ __forceinline__ void operator()(const f32x4 (&acc)[2][2][4][2], const pg8::Unit& u, int wr, int wc, int fr, int fq, const LAS float* scr) const {
;     ...
;             for (int m = 0; m < 4; ++m) { const int row = row0 + ai * 128 + m * 16; float r[8]; const float s_ = scr[ai * 128 + wr * 64 + m * 16 + fr];
;                 const float k_ = -LOG2E * s_, s2_ = s_ * s_;
; #pragma unroll
;                 for (int n = 0; n < 2; ++n)
; #pragma unroll
;                     for (int i = 0; i < 4; ++i) { const float g_ = acc[ai][0][m][n][i], u_ = acc[ai][1][m][n][i];
;                         r[n * 4 + i] = (g_ * u_) * (s2_ * __builtin_amdgcn_rcpf(1.0f + __builtin_amdgcn_exp2f(g_ * k_))); }
;                 typedef float f32x2_ __attribute__((ext_vector_type(2))); typedef __bf16 bf16x2_ __attribute__((ext_vector_type(2)));
;                 u32x4 w;
;                 { const f32x2_ a0 = {r[0], r[1]}, a1 = {r[2], r[3]}, a2 = {r[4], r[5]}, a3 = {r[6], r[7]};
;                   w.x = __builtin_bit_cast(unsigned, __builtin_convertvector(a0, bf16x2_)); w.y = __builtin_bit_cast(unsigned, __builtin_convertvector(a1, bf16x2_));
;                   w.z = __builtin_bit_cast(unsigned, __builtin_convertvector(a2, bf16x2_)); w.w = __builtin_bit_cast(unsigned, __builtin_convertvector(a3, bf16x2_)); }
;                 *(GAS u32x4*)(H + (size_t)row * ldc + col0) = w; }
	v_mul_f32_e32 v61, 0xbfb8aa3b, v77
	v_mul_f32_e32 v62, v52, v61
	v_mul_f32_e32 v63, v53, v61
	v_exp_f32_e32 v62, v62
	v_exp_f32_e32 v63, v63
	v_mul_f32_e32 v60, v77, v77
	v_pk_mul_f32 v[52:53], v[52:53], v[56:57]
	v_add_f32_e32 v62, 1.0, v62
	v_add_f32_e32 v63, 1.0, v63
	v_rcp_f32_e32 v62, v62
	v_rcp_f32_e32 v63, v63
	v_mul_f32_e32 v54, v54, v61
	v_mul_f32_e32 v55, v55, v61
	v_exp_f32_e32 v54, v54
	v_pk_mul_f32 v[56:57], v[60:61], v[62:63] op_sel_hi:[0,1]
	v_pk_mul_f32 v[52:53], v[52:53], v[56:57]
	v_mul_f32_e32 v56, v44, v61
	v_mul_f32_e32 v57, v45, v61
	v_exp_f32_e32 v56, v56
	v_exp_f32_e32 v57, v57
	v_pk_mul_f32 v[44:45], v[44:45], v[48:49]
	v_exp_f32_e32 v55, v55
	v_add_f32_e32 v56, 1.0, v56
	v_add_f32_e32 v57, 1.0, v57
	v_rcp_f32_e32 v56, v56
	v_rcp_f32_e32 v57, v57
	v_add_f32_e32 v54, 1.0, v54
	v_add_f32_e32 v55, 1.0, v55
	v_rcp_f32_e32 v54, v54
	v_pk_mul_f32 v[48:49], v[60:61], v[56:57] op_sel_hi:[0,1]
	v_pk_mul_f32 v[48:49], v[44:45], v[48:49]
	v_mul_f32_e32 v44, v46, v61
	v_mul_f32_e32 v45, v47, v61
	v_exp_f32_e32 v44, v44
	v_exp_f32_e32 v45, v45
	v_rcp_f32_e32 v55, v55
	v_add_u32_e32 v56, 0x90, v154
	v_add_f32_e32 v44, 1.0, v44
	v_add_f32_e32 v45, 1.0, v45
	v_rcp_f32_e32 v44, v44
	v_rcp_f32_e32 v45, v45
	v_pk_mul_f32 v[54:55], v[60:61], v[54:55] op_sel_hi:[0,1]
	v_pk_mul_f32 v[54:55], v[58:59], v[54:55]
	v_cvt_pk_bf16_f32 v46, v48, v49
	v_pk_mul_f32 v[44:45], v[60:61], v[44:45] op_sel_hi:[0,1]
	v_pk_mul_f32 v[50:51], v[50:51], v[44:45]
	v_mad_i64_i32 v[48:49], s[0:1], v56, s2, v[124:125]
	v_cvt_pk_bf16_f32 v44, v52, v53
	v_cvt_pk_bf16_f32 v45, v54, v55
	v_cvt_pk_bf16_f32 v47, v50, v51
	v_lshl_add_u64 v[48:49], v[48:49], 0, v[126:127]
	global_store_dwordx4 v[48:49], v[44:47], off
	ds_read2_b32 v[44:45], v155 offset0:160 offset1:176
	v_pk_mul_f32 v[26:27], v[22:23], v[26:27]
	v_pk_mul_f32 v[14:15], v[18:19], v[14:15]
	s_waitcnt lgkmcnt(0)
	v_mul_f32_e32 v48, 0xbfb8aa3b, v44
	v_mul_f32_e32 v46, v36, v48
	v_mul_f32_e32 v47, v37, v48
	v_exp_f32_e32 v46, v46
	v_exp_f32_e32 v47, v47
	v_mul_f32_e32 v44, v44, v44
	v_pk_mul_f32 v[36:37], v[36:37], v[40:41]
	v_add_f32_e32 v46, 1.0, v46
	v_add_f32_e32 v47, 1.0, v47
	v_rcp_f32_e32 v46, v46
	v_rcp_f32_e32 v47, v47
	v_mul_f32_e32 v38, v38, v48
	v_mul_f32_e32 v39, v39, v48
	v_exp_f32_e32 v38, v38
	v_pk_mul_f32 v[40:41], v[44:45], v[46:47] op_sel_hi:[0,1]
	v_pk_mul_f32 v[36:37], v[36:37], v[40:41]
	v_mul_f32_e32 v40, v28, v48
	v_mul_f32_e32 v41, v29, v48
	v_exp_f32_e32 v40, v40
	v_exp_f32_e32 v41, v41
	v_pk_mul_f32 v[28:29], v[28:29], v[32:33]
	v_exp_f32_e32 v39, v39
	v_add_f32_e32 v40, 1.0, v40
	v_add_f32_e32 v41, 1.0, v41
	v_rcp_f32_e32 v40, v40
	v_rcp_f32_e32 v41, v41
	v_add_f32_e32 v38, 1.0, v38
	v_add_f32_e32 v39, 1.0, v39
	v_rcp_f32_e32 v38, v38
	v_pk_mul_f32 v[32:33], v[44:45], v[40:41] op_sel_hi:[0,1]
	v_pk_mul_f32 v[32:33], v[28:29], v[32:33]
	v_mul_f32_e32 v28, v30, v48
	v_mul_f32_e32 v29, v31, v48
	v_exp_f32_e32 v28, v28
	v_exp_f32_e32 v29, v29
	v_rcp_f32_e32 v39, v39
	v_add_u32_e32 v40, 0xa0, v154
	v_add_f32_e32 v28, 1.0, v28
	v_add_f32_e32 v29, 1.0, v29
	v_rcp_f32_e32 v28, v28
	v_rcp_f32_e32 v29, v29
	v_pk_mul_f32 v[38:39], v[44:45], v[38:39] op_sel_hi:[0,1]
	v_pk_mul_f32 v[38:39], v[42:43], v[38:39]
	v_cvt_pk_bf16_f32 v30, v32, v33
	v_pk_mul_f32 v[28:29], v[44:45], v[28:29] op_sel_hi:[0,1]
	v_pk_mul_f32 v[34:35], v[34:35], v[28:29]
	v_mad_i64_i32 v[32:33], s[0:1], v40, s2, v[124:125]
	v_cvt_pk_bf16_f32 v28, v36, v37
	v_cvt_pk_bf16_f32 v29, v38, v39
	v_cvt_pk_bf16_f32 v31, v34, v35
	v_lshl_add_u64 v[32:33], v[32:33], 0, v[126:127]
	global_store_dwordx4 v[32:33], v[28:31], off
	s_nop 1
	v_mul_f32_e32 v29, 0xbfb8aa3b, v45
	v_mul_f32_e32 v30, v20, v29
	v_mul_f32_e32 v31, v21, v29
	v_exp_f32_e32 v30, v30
	v_exp_f32_e32 v31, v31
	v_mul_f32_e32 v28, v45, v45
	v_pk_mul_f32 v[20:21], v[20:21], v[24:25]
	v_add_f32_e32 v30, 1.0, v30
	v_add_f32_e32 v31, 1.0, v31
	v_rcp_f32_e32 v30, v30
	v_rcp_f32_e32 v31, v31
	v_mul_f32_e32 v22, v22, v29
	v_mul_f32_e32 v23, v23, v29
	v_exp_f32_e32 v22, v22
	v_pk_mul_f32 v[24:25], v[28:29], v[30:31] op_sel_hi:[0,1]
	v_pk_mul_f32 v[20:21], v[20:21], v[24:25]
	v_mul_f32_e32 v24, v16, v29
	v_mul_f32_e32 v25, v17, v29
	v_exp_f32_e32 v24, v24
	v_exp_f32_e32 v25, v25
	v_exp_f32_e32 v23, v23
	v_add_f32_e32 v22, 1.0, v22
	v_add_f32_e32 v24, 1.0, v24
	v_add_f32_e32 v25, 1.0, v25
	v_rcp_f32_e32 v24, v24
	v_rcp_f32_e32 v25, v25
	v_add_f32_e32 v23, 1.0, v23
	v_rcp_f32_e32 v22, v22
	v_rcp_f32_e32 v23, v23
	v_pk_mul_f32 v[16:17], v[28:29], v[24:25] op_sel_hi:[0,1]
	v_pk_mul_f32 v[16:17], v[12:13], v[16:17]
	v_mul_f32_e32 v12, v18, v29
	v_mul_f32_e32 v13, v19, v29
	v_exp_f32_e32 v12, v12
	v_exp_f32_e32 v13, v13
	v_pk_mul_f32 v[22:23], v[28:29], v[22:23] op_sel_hi:[0,1]
	v_add_u32_e32 v24, 0xb0, v154
	v_add_f32_e32 v12, 1.0, v12
	v_add_f32_e32 v13, 1.0, v13
	v_rcp_f32_e32 v12, v12
	v_rcp_f32_e32 v13, v13
	v_pk_mul_f32 v[22:23], v[26:27], v[22:23]
	v_pk_mul_f32 v[12:13], v[28:29], v[12:13] op_sel_hi:[0,1]
	v_pk_mul_f32 v[18:19], v[14:15], v[12:13]
	v_cvt_pk_bf16_f32 v14, v16, v17
	v_mad_i64_i32 v[16:17], s[0:1], v24, s2, v[124:125]
	v_cvt_pk_bf16_f32 v12, v20, v21
	v_cvt_pk_bf16_f32 v13, v22, v23
	v_cvt_pk_bf16_f32 v15, v18, v19
	v_lshl_add_u64 v[16:17], v[16:17], 0, v[126:127]
	global_store_dwordx4 v[16:17], v[12:15], off
	s_and_saveexec_b64 s[0:1], s[24:25]
	s_cbranch_execz .LBB0_1898
	s_waitcnt vmcnt(8)
	v_mov_b32_e32 v12, v4
	v_mov_b32_e32 v13, v8
	v_mov_b32_e32 v14, v5
	v_mov_b32_e32 v15, v9
	v_pk_add_f32 v[12:13], v[12:13], v[14:15]
	v_mov_b32_e32 v14, v6
	v_mov_b32_e32 v15, v10
	v_mov_b32_e32 v16, v7
	v_mov_b32_e32 v17, v11
	v_pk_add_f32 v[14:15], v[14:15], v[16:17]
	s_lshl_b32 s2, s45, 10
	v_pk_add_f32 v[12:13], v[12:13], v[14:15]
	s_and_b32 s2, s2, 0x400
	v_add_f32_e32 v12, v12, v13
	v_fmamk_f32 v12, v12, 0x3a000000, v241
	v_rsq_f32_e32 v12, v12
	v_add_u32_e32 v13, s2, v152
	ds_write_b32 v13, v12
